# back-edge rotation (7.11) in the P1 K-loop: counter/pointer updates and the loop test moved in front of the loop-back barrier, which becomes the loop head; P3 loop-header RS test shortened to 3 SALU
# baseline (speedup 1.0000x reference)
; #define PG8_LAS __attribute__((address_space(3)))
; #define PG8_STAGE(bufoff, gbase, voff) do { _Pragma("unroll") for (int _i = 0; _i < 2; ++_i) \
;         __builtin_amdgcn_global_load_lds((const unsigned*)((const char*)(gbase) + (voff)[_i]), (PG8_LAS unsigned*)(lds + (bufoff) + ldsw + _i * 8192), 16, 0, 0); } while (0)
; #define PG8_WAIT_V(n) asm volatile("s_waitcnt vmcnt(" #n ")" ::: "memory")
; #define PG8_WAIT_L(n) asm volatile("s_waitcnt lgkmcnt(" #n ")" ::: "memory")
; template <class Epi, class Sched, bool ALIGN_EPI = false, bool SP2 = false, bool RS = false, bool BPRE = false>
; __device__ __forceinline__ void gemm_phase(PG8_LAS unsigned char* lds, const Gemm g, const Sched& S, const Epi& E, const float* rs_ss = nullptr, PG8_LAS float* rs_tab = nullptr) {
;     ...
;         const char* nA = has_next ? (const char*)g.A + (size_t)nxt.pm * tstep : cA; const char* nB = has_next ? (const char*)g.Bt + (size_t)nxt.pn * tstep : cB;
;         for (int t = 0; t < nt; t += 2) {
;             const bool last = (t == nt - 2);
;             if constexpr (RS) { if (t == 16 || t == 32) { const PG8_LAS float* tp = rs_tab + (ui & 1) * 768 + (t == 32 ? 256 : 0);
;                 _Pragma("unroll") for (int a = 0; a < 2; ++a) _Pragma("unroll") for (int m = 0; m < 4; ++m) { const float f = tp[a * HALF + wr * 64 + m * 16 + fr];
;                     _Pragma("unroll") for (int b = 0; b < 2; ++b) _Pragma("unroll") for (int n = 0; n < 2; ++n) acc[a][b][m][n] = acc[a][b][m][n] * f; } } }
;             const char* a1 = cA + (size_t)(t + 1) * kstep;
;             const char* a2 = last ? nA : cA + (size_t)(t + 2) * kstep; const char* b2 = last ? nB : cB + (size_t)(t + 2) * kstep;
;             const char* a3 = a2 + kstep; const char* b3 = b2 + kstep;
;             if (last && has_next) S.a_ready(nxt);
;             if constexpr (SP2) {
;             PG8_LDB(B0, 0, 0); PG8_LDB(B1, 0, 1); PG8_SCHED; PG8_LDA(At, 0, 0); PG8_STAGE(PG8_SA(1, 1), a1 + hstep, voffA);
;             PG8_WAIT_V(8); PG8_WAIT_L(0); PG8_BAR; PG8_MMA(0, 0, At, B0); PG8_MMA(0, 1, At, B1); PG8_BAR; PG8_SCHED;
;             PG8_LDA(At, 0, 1); PG8_STAGE(PG8_SB(0, 0), b2, voffB); PG8_STAGE(PG8_SB(0, 1), b2 + hstep, voffB); PG8_STAGE(PG8_SA(0, 0), a2, voffA);
;             PG8_WAIT_V(8); PG8_WAIT_L(0); PG8_BAR; PG8_MMA(1, 0, At, B0); PG8_MMA(1, 1, At, B1); PG8_BAR; PG8_SCHED;
.LBB0_195:
	s_ashr_i32 s19, s18, 31
	s_lshl_b64 s[20:21], s[18:19], 20
	s_add_u32 s20, s30, s20
	s_addc_u32 s21, s31, s21
	s_and_b64 s[44:45], s[6:7], exec
	s_cselect_b32 s5, s21, s57
	s_cselect_b32 s19, s20, s56
	s_ashr_i32 s17, s16, 31
	s_lshl_b64 s[44:45], s[16:17], 20
	s_add_u32 s44, s24, s44
	s_addc_u32 s45, s25, s45
	s_and_b64 s[60:61], s[6:7], exec
	s_cselect_b32 s17, s45, s59
	s_cselect_b32 s47, s44, s58
	s_add_u32 s56, s56, 0x84000
	s_addc_u32 s57, s57, 0
	s_add_u32 s87, s58, 0x8000
	s_addc_u32 s88, s59, 0
	s_mov_b32 s89, -2
	s_waitcnt lgkmcnt(0)
	ds_read_b128 v[130:133], v161
	ds_read_b128 v[134:137], v161 offset:1024
	ds_read_b128 v[152:155], v161 offset:2048
	ds_read_b128 v[156:159], v161 offset:3072
	ds_read_b128 v[166:169], v162
	ds_read_b128 v[170:173], v162 offset:1024
	ds_read_b128 v[174:177], v162 offset:2048
	ds_read_b128 v[182:185], v162 offset:3072
	s_add_u32 s58, s56, 0xfff84000
	s_addc_u32 s59, s57, -1
	s_cmp_eq_u32 s89, 28
	s_cselect_b32 s70, s19, s58
	s_cselect_b32 s71, s5, s59
	s_cselect_b32 s60, s47, s87
	s_cselect_b32 s61, s17, s88
	s_add_u32 s58, s70, 0x4000
	s_addc_u32 s59, s71, 0
	v_lshl_add_u64 v[178:179], s[56:57], 0, v[138:139]
	s_add_i32 m0, s72, 0xc000
	ds_read_b128 v[186:189], v163
	ds_read_b128 v[190:193], v163 offset:1024
	ds_read_b128 v[194:197], v163 offset:2048
	ds_read_b128 v[198:201], v163 offset:3072
	ds_read_b128 v[202:205], v163 offset:4096
	ds_read_b128 v[206:209], v163 offset:5120
	ds_read_b128 v[210:213], v163 offset:6144
	ds_read_b128 v[214:217], v163 offset:7168
	global_load_lds_dwordx4 v[178:179], off
	v_lshl_add_u64 v[178:179], s[56:57], 0, v[146:147]
	s_add_i32 m0, s72, 0xe000
	s_nop 0
	global_load_lds_dwordx4 v[178:179], off
	s_waitcnt vmcnt(8)
	s_waitcnt lgkmcnt(0)
	s_barrier
	s_setprio 1
	s_waitcnt lgkmcnt(0)
	v_mfma_f32_16x16x32_bf16 v[126:129], v[130:133], v[186:189], 0
	v_mfma_f32_16x16x32_bf16 v[122:125], v[152:155], v[186:189], 0
	v_mfma_f32_16x16x32_bf16 v[110:113], v[130:133], v[194:197], 0
	v_mfma_f32_16x16x32_bf16 v[106:109], v[152:155], v[194:197], 0
	v_mfma_f32_16x16x32_bf16 v[94:97], v[130:133], v[202:205], 0
	v_mfma_f32_16x16x32_bf16 v[90:93], v[152:155], v[202:205], 0
	v_mfma_f32_16x16x32_bf16 v[78:81], v[130:133], v[210:213], 0
	v_mfma_f32_16x16x32_bf16 v[74:77], v[152:155], v[210:213], 0
	v_mfma_f32_16x16x32_bf16 v[126:129], v[134:137], v[190:193], v[126:129]
	v_mfma_f32_16x16x32_bf16 v[122:125], v[156:159], v[190:193], v[122:125]
	v_mfma_f32_16x16x32_bf16 v[110:113], v[134:137], v[198:201], v[110:113]
	v_mfma_f32_16x16x32_bf16 v[106:109], v[156:159], v[198:201], v[106:109]
	v_mfma_f32_16x16x32_bf16 v[94:97], v[134:137], v[206:209], v[94:97]
	v_mfma_f32_16x16x32_bf16 v[90:93], v[156:159], v[206:209], v[90:93]
	v_mfma_f32_16x16x32_bf16 v[78:81], v[134:137], v[214:217], v[78:81]
	v_mfma_f32_16x16x32_bf16 v[74:77], v[156:159], v[214:217], v[74:77]
	s_setprio 0
	s_setprio 1
	v_mfma_f32_16x16x32_bf16 v[118:121], v[166:169], v[186:189], 0
	v_mfma_f32_16x16x32_bf16 v[114:117], v[174:177], v[186:189], 0
	v_mfma_f32_16x16x32_bf16 v[102:105], v[166:169], v[194:197], 0
	v_mfma_f32_16x16x32_bf16 v[98:101], v[174:177], v[194:197], 0
	v_mfma_f32_16x16x32_bf16 v[86:89], v[166:169], v[202:205], 0
	v_mfma_f32_16x16x32_bf16 v[82:85], v[174:177], v[202:205], 0
	v_mfma_f32_16x16x32_bf16 v[70:73], v[166:169], v[210:213], 0
	v_mfma_f32_16x16x32_bf16 v[66:69], v[174:177], v[210:213], 0
	v_mfma_f32_16x16x32_bf16 v[118:121], v[170:173], v[190:193], v[118:121]
	v_mfma_f32_16x16x32_bf16 v[114:117], v[182:185], v[190:193], v[114:117]
	v_mfma_f32_16x16x32_bf16 v[102:105], v[170:173], v[198:201], v[102:105]
	v_mfma_f32_16x16x32_bf16 v[98:101], v[182:185], v[198:201], v[98:101]
	v_mfma_f32_16x16x32_bf16 v[86:89], v[170:173], v[206:209], v[86:89]
	v_mfma_f32_16x16x32_bf16 v[82:85], v[182:185], v[206:209], v[82:85]
	v_mfma_f32_16x16x32_bf16 v[70:73], v[170:173], v[214:217], v[70:73]
	v_mfma_f32_16x16x32_bf16 v[66:69], v[182:185], v[214:217], v[66:69]
	s_setprio 0
	s_barrier
	s_add_i32 s90, s83, s15
	v_lshl_add_u64 v[178:179], s[60:61], 0, v[138:139]
	s_mov_b32 m0, s90
	ds_read_b128 v[186:189], v163 offset:16384
	ds_read_b128 v[190:193], v163 offset:17408
	ds_read_b128 v[194:197], v163 offset:18432
	ds_read_b128 v[198:201], v163 offset:19456
	ds_read_b128 v[202:205], v163 offset:20480
	ds_read_b128 v[206:209], v163 offset:21504
	ds_read_b128 v[210:213], v163 offset:22528
	ds_read_b128 v[214:217], v163 offset:23552
	global_load_lds_dwordx4 v[178:179], off
	s_add_i32 m0, s90, 0x2000
	s_add_u32 s90, s60, 0x80000
	v_lshl_add_u64 v[178:179], s[60:61], 0, v[140:141]
	s_addc_u32 s91, s61, 0
	s_add_i32 s92, s86, s15
	global_load_lds_dwordx4 v[178:179], off
	v_lshl_add_u64 v[178:179], s[90:91], 0, v[138:139]
	s_mov_b32 m0, s92
	s_nop 0
	global_load_lds_dwordx4 v[178:179], off
	v_lshl_add_u64 v[178:179], s[90:91], 0, v[140:141]
	s_add_i32 m0, s92, 0x2000
	s_nop 0
	global_load_lds_dwordx4 v[178:179], off
	v_lshl_add_u64 v[178:179], s[70:71], 0, v[138:139]
	s_mov_b32 m0, s72
	s_nop 0
	global_load_lds_dwordx4 v[178:179], off
	v_lshl_add_u64 v[178:179], s[70:71], 0, v[140:141]
	s_mov_b32 m0, s73
	s_nop 0
	global_load_lds_dwordx4 v[178:179], off
	s_waitcnt vmcnt(8)
	s_waitcnt lgkmcnt(0)
	s_barrier
; #define PG8_STAGE(bufoff, gbase, voff) do { _Pragma("unroll") for (int _i = 0; _i < 2; ++_i) \
;         __builtin_amdgcn_global_load_lds((const unsigned*)((const char*)(gbase) + (voff)[_i]), (PG8_LAS unsigned*)(lds + (bufoff) + ldsw + _i * 8192), 16, 0, 0); } while (0)
; #define PG8_LDA(dst, b, h) do { _Pragma("unroll") for (int m = 0; m < 4; ++m) _Pragma("unroll") for (int k = 0; k < 2; ++k) dst[m][k] = *(const PG8_LAS bf16x8*)(lds + PG8_SA(b, h) + aoff + m * 2048 + k * 1024); } while (0)
; #define PG8_LDB(dst, b, h) do { _Pragma("unroll") for (int n = 0; n < 2; ++n) _Pragma("unroll") for (int k = 0; k < 2; ++k) dst[n][k] = *(const PG8_LAS bf16x8*)(lds + PG8_SB(b, h) + boff + n * 2048 + k * 1024); } while (0)
; #define PG8_MMA(ai, bj, At, Bt) do { __builtin_amdgcn_s_setprio(1); _Pragma("unroll") for (int m = 0; m < 4; ++m) _Pragma("unroll") for (int n = 0; n < 2; ++n) _Pragma("unroll") for (int k = 0; k < 2; ++k) \
;         acc[ai][bj][m][n] = __builtin_amdgcn_mfma_f32_16x16x32_bf16(Bt[n][k], At[m][k], acc[ai][bj][m][n], 0, 0, 0); __builtin_amdgcn_s_setprio(0); } while (0)
; #define PG8_WAIT_V(n) asm volatile("s_waitcnt vmcnt(" #n ")" ::: "memory")
; #define PG8_WAIT_L(n) asm volatile("s_waitcnt lgkmcnt(" #n ")" ::: "memory")
; #define PG8_BAR __builtin_amdgcn_s_barrier()
; #define PG8_SCHED __builtin_amdgcn_sched_barrier(0)
; template <class Epi, class Sched, bool ALIGN_EPI = false, bool SP2 = false, bool RS = false, bool BPRE = false>
; __device__ __forceinline__ void gemm_phase(PG8_LAS unsigned char* lds, const Gemm g, const Sched& S, const Epi& E, const float* rs_ss = nullptr, PG8_LAS float* rs_tab = nullptr) {
;     ...
;             PG8_WAIT_V(8); PG8_WAIT_L(0); PG8_BAR; PG8_MMA(1, 0, At, B0); PG8_MMA(1, 1, At, B1); PG8_BAR; PG8_SCHED;
;             PG8_LDB(B0, 1, 0); PG8_LDB(B1, 1, 1); PG8_SCHED; PG8_LDA(At, 1, 0); PG8_STAGE(PG8_SA(0, 1), a2 + hstep, voffA);
;             PG8_WAIT_V(8); PG8_WAIT_L(0); PG8_BAR; PG8_MMA(0, 0, At, B0); PG8_MMA(0, 1, At, B1); PG8_BAR; PG8_SCHED;
;             PG8_LDA(At, 1, 1); PG8_STAGE(PG8_SB(1, 0), b3, voffB); PG8_STAGE(PG8_SB(1, 1), b3 + hstep, voffB); PG8_STAGE(PG8_SA(1, 0), a3, voffA);
;             PG8_WAIT_V(8); PG8_WAIT_L(0); PG8_BAR; PG8_MMA(1, 0, At, B0); PG8_MMA(1, 1, At, B1); PG8_BAR; PG8_SCHED;
	s_setprio 1
	s_waitcnt lgkmcnt(0)
	v_mfma_f32_16x16x32_bf16 v[62:65], v[130:133], v[186:189], 0
	v_mfma_f32_16x16x32_bf16 v[58:61], v[152:155], v[186:189], 0
	v_mfma_f32_16x16x32_bf16 v[46:49], v[130:133], v[194:197], 0
	v_mfma_f32_16x16x32_bf16 v[42:45], v[152:155], v[194:197], 0
	v_mfma_f32_16x16x32_bf16 v[30:33], v[130:133], v[202:205], 0
	v_mfma_f32_16x16x32_bf16 v[26:29], v[152:155], v[202:205], 0
	v_mfma_f32_16x16x32_bf16 v[14:17], v[130:133], v[210:213], 0
	v_mfma_f32_16x16x32_bf16 v[10:13], v[152:155], v[210:213], 0
	v_mfma_f32_16x16x32_bf16 v[62:65], v[134:137], v[190:193], v[62:65]
	v_mfma_f32_16x16x32_bf16 v[58:61], v[156:159], v[190:193], v[58:61]
	v_mfma_f32_16x16x32_bf16 v[46:49], v[134:137], v[198:201], v[46:49]
	v_mfma_f32_16x16x32_bf16 v[42:45], v[156:159], v[198:201], v[42:45]
	v_mfma_f32_16x16x32_bf16 v[30:33], v[134:137], v[206:209], v[30:33]
	v_mfma_f32_16x16x32_bf16 v[26:29], v[156:159], v[206:209], v[26:29]
	v_mfma_f32_16x16x32_bf16 v[14:17], v[134:137], v[214:217], v[14:17]
	v_mfma_f32_16x16x32_bf16 v[10:13], v[156:159], v[214:217], v[10:13]
	s_setprio 0
	s_setprio 1
	v_mfma_f32_16x16x32_bf16 v[54:57], v[166:169], v[186:189], 0
	v_mfma_f32_16x16x32_bf16 v[50:53], v[174:177], v[186:189], 0
	v_mfma_f32_16x16x32_bf16 v[38:41], v[166:169], v[194:197], 0
	v_mfma_f32_16x16x32_bf16 v[34:37], v[174:177], v[194:197], 0
	v_mfma_f32_16x16x32_bf16 v[22:25], v[166:169], v[202:205], 0
	v_mfma_f32_16x16x32_bf16 v[18:21], v[174:177], v[202:205], 0
	v_mfma_f32_16x16x32_bf16 v[6:9], v[166:169], v[210:213], 0
	v_mfma_f32_16x16x32_bf16 v[2:5], v[174:177], v[210:213], 0
	v_mfma_f32_16x16x32_bf16 v[54:57], v[170:173], v[190:193], v[54:57]
	v_mfma_f32_16x16x32_bf16 v[50:53], v[182:185], v[190:193], v[50:53]
	v_mfma_f32_16x16x32_bf16 v[38:41], v[170:173], v[198:201], v[38:41]
	v_mfma_f32_16x16x32_bf16 v[34:37], v[182:185], v[198:201], v[34:37]
	v_mfma_f32_16x16x32_bf16 v[22:25], v[170:173], v[206:209], v[22:25]
	v_mfma_f32_16x16x32_bf16 v[18:21], v[182:185], v[206:209], v[18:21]
	v_mfma_f32_16x16x32_bf16 v[6:9], v[170:173], v[214:217], v[6:9]
	v_mfma_f32_16x16x32_bf16 v[2:5], v[182:185], v[214:217], v[2:5]
	s_setprio 0
	s_barrier
	s_add_i32 s90, 0, 0x18000
	v_add_u32_e32 v143, s90, v160
	s_add_i32 s91, 0, 0x1c000
	ds_read_b128 v[130:133], v143
	ds_read_b128 v[134:137], v143 offset:1024
	ds_read_b128 v[152:155], v143 offset:2048
	ds_read_b128 v[156:159], v143 offset:3072
	v_add_u32_e32 v143, s91, v160
	ds_read_b128 v[166:169], v143
	ds_read_b128 v[170:173], v143 offset:1024
	ds_read_b128 v[174:177], v143 offset:2048
	ds_read_b128 v[182:185], v143 offset:3072
	s_add_u32 s70, s70, 0x80000
	s_addc_u32 s71, s71, 0
	s_mov_b32 m0, s74
	v_lshl_add_u64 v[178:179], s[70:71], 0, v[138:139]
	ds_read_b128 v[186:189], v163 offset:32768
	ds_read_b128 v[190:193], v163 offset:33792
	ds_read_b128 v[194:197], v163 offset:34816
	ds_read_b128 v[198:201], v163 offset:35840
	ds_read_b128 v[202:205], v163 offset:36864
	ds_read_b128 v[206:209], v163 offset:37888
	ds_read_b128 v[210:213], v163 offset:38912
	ds_read_b128 v[214:217], v163 offset:39936
	global_load_lds_dwordx4 v[178:179], off
	v_lshl_add_u64 v[178:179], s[70:71], 0, v[140:141]
	s_mov_b32 m0, s75
	s_nop 0
	global_load_lds_dwordx4 v[178:179], off
	s_waitcnt vmcnt(8)
	s_waitcnt lgkmcnt(0)
	s_barrier
	s_setprio 1
	s_waitcnt lgkmcnt(0)
	v_mfma_f32_16x16x32_bf16 v[126:129], v[130:133], v[186:189], v[126:129]
	v_mfma_f32_16x16x32_bf16 v[122:125], v[152:155], v[186:189], v[122:125]
	v_mfma_f32_16x16x32_bf16 v[110:113], v[130:133], v[194:197], v[110:113]
	v_mfma_f32_16x16x32_bf16 v[106:109], v[152:155], v[194:197], v[106:109]
	v_mfma_f32_16x16x32_bf16 v[94:97], v[130:133], v[202:205], v[94:97]
	v_mfma_f32_16x16x32_bf16 v[90:93], v[152:155], v[202:205], v[90:93]
	v_mfma_f32_16x16x32_bf16 v[78:81], v[130:133], v[210:213], v[78:81]
	v_mfma_f32_16x16x32_bf16 v[74:77], v[152:155], v[210:213], v[74:77]
	v_mfma_f32_16x16x32_bf16 v[126:129], v[134:137], v[190:193], v[126:129]
	v_mfma_f32_16x16x32_bf16 v[122:125], v[156:159], v[190:193], v[122:125]
	v_mfma_f32_16x16x32_bf16 v[110:113], v[134:137], v[198:201], v[110:113]
	v_mfma_f32_16x16x32_bf16 v[106:109], v[156:159], v[198:201], v[106:109]
	v_mfma_f32_16x16x32_bf16 v[94:97], v[134:137], v[206:209], v[94:97]
	v_mfma_f32_16x16x32_bf16 v[90:93], v[156:159], v[206:209], v[90:93]
	v_mfma_f32_16x16x32_bf16 v[78:81], v[134:137], v[214:217], v[78:81]
	v_mfma_f32_16x16x32_bf16 v[74:77], v[156:159], v[214:217], v[74:77]
	s_setprio 0
	s_setprio 1
	v_mfma_f32_16x16x32_bf16 v[118:121], v[166:169], v[186:189], v[118:121]
	v_mfma_f32_16x16x32_bf16 v[114:117], v[174:177], v[186:189], v[114:117]
	v_mfma_f32_16x16x32_bf16 v[102:105], v[166:169], v[194:197], v[102:105]
	v_mfma_f32_16x16x32_bf16 v[98:101], v[174:177], v[194:197], v[98:101]
	v_mfma_f32_16x16x32_bf16 v[86:89], v[166:169], v[202:205], v[86:89]
	v_mfma_f32_16x16x32_bf16 v[82:85], v[174:177], v[202:205], v[82:85]
	v_mfma_f32_16x16x32_bf16 v[70:73], v[166:169], v[210:213], v[70:73]
	v_mfma_f32_16x16x32_bf16 v[66:69], v[174:177], v[210:213], v[66:69]
	v_mfma_f32_16x16x32_bf16 v[118:121], v[170:173], v[190:193], v[118:121]
	v_mfma_f32_16x16x32_bf16 v[114:117], v[182:185], v[190:193], v[114:117]
	v_mfma_f32_16x16x32_bf16 v[102:105], v[170:173], v[198:201], v[102:105]
	v_mfma_f32_16x16x32_bf16 v[98:101], v[182:185], v[198:201], v[98:101]
	v_mfma_f32_16x16x32_bf16 v[86:89], v[170:173], v[206:209], v[86:89]
	v_mfma_f32_16x16x32_bf16 v[82:85], v[182:185], v[206:209], v[82:85]
	v_mfma_f32_16x16x32_bf16 v[70:73], v[170:173], v[214:217], v[70:73]
	v_mfma_f32_16x16x32_bf16 v[66:69], v[182:185], v[214:217], v[66:69]
	s_setprio 0
	s_barrier
; #define PG8_LAS __attribute__((address_space(3)))
; #define PG8_STAGE(bufoff, gbase, voff) do { _Pragma("unroll") for (int _i = 0; _i < 2; ++_i) \
;         __builtin_amdgcn_global_load_lds((const unsigned*)((const char*)(gbase) + (voff)[_i]), (PG8_LAS unsigned*)(lds + (bufoff) + ldsw + _i * 8192), 16, 0, 0); } while (0)
; #define PG8_LDA(dst, b, h) do { _Pragma("unroll") for (int m = 0; m < 4; ++m) _Pragma("unroll") for (int k = 0; k < 2; ++k) dst[m][k] = *(const PG8_LAS bf16x8*)(lds + PG8_SA(b, h) + aoff + m * 2048 + k * 1024); } while (0)
; #define PG8_WAIT_V(n) asm volatile("s_waitcnt vmcnt(" #n ")" ::: "memory")
; #define PG8_BAR __builtin_amdgcn_s_barrier()
; template <class Epi, class Sched, bool ALIGN_EPI = false, bool SP2 = false, bool RS = false, bool BPRE = false>
; __device__ __forceinline__ void gemm_phase(PG8_LAS unsigned char* lds, const Gemm g, const Sched& S, const Epi& E, const float* rs_ss = nullptr, PG8_LAS float* rs_tab = nullptr) {
;     ...
;         for (int t = 0; t < nt; t += 2) {
;             const bool last = (t == nt - 2);
;             if constexpr (RS) { if (t == 16 || t == 32) { const PG8_LAS float* tp = rs_tab + (ui & 1) * 768 + (t == 32 ? 256 : 0);
;                 _Pragma("unroll") for (int a = 0; a < 2; ++a) _Pragma("unroll") for (int m = 0; m < 4; ++m) { const float f = tp[a * HALF + wr * 64 + m * 16 + fr];
;                     _Pragma("unroll") for (int b = 0; b < 2; ++b) _Pragma("unroll") for (int n = 0; n < 2; ++n) acc[a][b][m][n] = acc[a][b][m][n] * f; } } }
;             const char* a1 = cA + (size_t)(t + 1) * kstep;
;             const char* a2 = last ? nA : cA + (size_t)(t + 2) * kstep; const char* b2 = last ? nB : cB + (size_t)(t + 2) * kstep;
;             const char* a3 = a2 + kstep; const char* b3 = b2 + kstep;
;             if (last && has_next) S.a_ready(nxt);
;             if constexpr (SP2) {
;             PG8_LDB(B0, 0, 0); PG8_LDB(B1, 0, 1); PG8_SCHED; PG8_LDA(At, 0, 0); PG8_STAGE(PG8_SA(1, 1), a1 + hstep, voffA);
;             PG8_WAIT_V(8); PG8_WAIT_L(0); PG8_BAR; PG8_MMA(0, 0, At, B0); PG8_MMA(0, 1, At, B1); PG8_BAR; PG8_SCHED;
;     ...
;             PG8_LDA(At, 1, 1); PG8_STAGE(PG8_SB(1, 0), b3, voffB); PG8_STAGE(PG8_SB(1, 1), b3 + hstep, voffB); PG8_STAGE(PG8_SA(1, 0), a3, voffA);
;             PG8_WAIT_V(8); PG8_WAIT_L(0); PG8_BAR; PG8_MMA(1, 0, At, B0); PG8_MMA(1, 1, At, B1); PG8_BAR; PG8_SCHED;
	s_add_u32 s70, s60, 0x4000
	s_addc_u32 s71, s61, 0
	s_add_i32 s90, s90, s15
	v_lshl_add_u64 v[178:179], s[70:71], 0, v[138:139]
	s_mov_b32 m0, s90
	ds_read_b128 v[186:189], v163 offset:49152
	ds_read_b128 v[190:193], v163 offset:50176
	ds_read_b128 v[194:197], v163 offset:51200
	ds_read_b128 v[198:201], v163 offset:52224
	ds_read_b128 v[202:205], v163 offset:53248
	ds_read_b128 v[206:209], v163 offset:54272
	ds_read_b128 v[210:213], v163 offset:55296
	ds_read_b128 v[214:217], v163 offset:56320
	global_load_lds_dwordx4 v[178:179], off
	s_add_i32 m0, s90, 0x2000
	s_add_u32 s60, s60, 0x84000
	v_lshl_add_u64 v[178:179], s[70:71], 0, v[140:141]
	s_addc_u32 s61, s61, 0
	s_add_i32 s70, s91, s15
	global_load_lds_dwordx4 v[178:179], off
	v_lshl_add_u64 v[178:179], s[60:61], 0, v[138:139]
	s_mov_b32 m0, s70
	s_nop 0
	global_load_lds_dwordx4 v[178:179], off
	v_lshl_add_u64 v[178:179], s[60:61], 0, v[140:141]
	s_add_i32 m0, s70, 0x2000
	s_nop 0
	global_load_lds_dwordx4 v[178:179], off
	v_lshl_add_u64 v[178:179], s[58:59], 0, v[138:139]
	s_mov_b32 m0, s79
	s_nop 0
	global_load_lds_dwordx4 v[178:179], off
	v_lshl_add_u64 v[178:179], s[58:59], 0, v[140:141]
	s_mov_b32 m0, s80
	s_nop 0
	global_load_lds_dwordx4 v[178:179], off
	s_waitcnt vmcnt(8)
	s_waitcnt lgkmcnt(0)
	s_barrier
	s_setprio 1
	s_waitcnt lgkmcnt(0)
	v_mfma_f32_16x16x32_bf16 v[62:65], v[130:133], v[186:189], v[62:65]
	v_mfma_f32_16x16x32_bf16 v[58:61], v[152:155], v[186:189], v[58:61]
	v_mfma_f32_16x16x32_bf16 v[46:49], v[130:133], v[194:197], v[46:49]
	v_mfma_f32_16x16x32_bf16 v[42:45], v[152:155], v[194:197], v[42:45]
	v_mfma_f32_16x16x32_bf16 v[30:33], v[130:133], v[202:205], v[30:33]
	v_mfma_f32_16x16x32_bf16 v[26:29], v[152:155], v[202:205], v[26:29]
	v_mfma_f32_16x16x32_bf16 v[14:17], v[130:133], v[210:213], v[14:17]
	v_mfma_f32_16x16x32_bf16 v[10:13], v[152:155], v[210:213], v[10:13]
	v_mfma_f32_16x16x32_bf16 v[62:65], v[134:137], v[190:193], v[62:65]
	v_mfma_f32_16x16x32_bf16 v[58:61], v[156:159], v[190:193], v[58:61]
	v_mfma_f32_16x16x32_bf16 v[46:49], v[134:137], v[198:201], v[46:49]
	v_mfma_f32_16x16x32_bf16 v[42:45], v[156:159], v[198:201], v[42:45]
	v_mfma_f32_16x16x32_bf16 v[30:33], v[134:137], v[206:209], v[30:33]
	v_mfma_f32_16x16x32_bf16 v[26:29], v[156:159], v[206:209], v[26:29]
	v_mfma_f32_16x16x32_bf16 v[14:17], v[134:137], v[214:217], v[14:17]
	v_mfma_f32_16x16x32_bf16 v[10:13], v[156:159], v[214:217], v[10:13]
	s_setprio 0
	s_setprio 1
	v_mfma_f32_16x16x32_bf16 v[54:57], v[166:169], v[186:189], v[54:57]
	v_mfma_f32_16x16x32_bf16 v[50:53], v[174:177], v[186:189], v[50:53]
	v_mfma_f32_16x16x32_bf16 v[38:41], v[166:169], v[194:197], v[38:41]
	v_mfma_f32_16x16x32_bf16 v[34:37], v[174:177], v[194:197], v[34:37]
	v_mfma_f32_16x16x32_bf16 v[22:25], v[166:169], v[202:205], v[22:25]
	v_mfma_f32_16x16x32_bf16 v[18:21], v[174:177], v[202:205], v[18:21]
	v_mfma_f32_16x16x32_bf16 v[6:9], v[166:169], v[210:213], v[6:9]
	v_mfma_f32_16x16x32_bf16 v[2:5], v[174:177], v[210:213], v[2:5]
	v_mfma_f32_16x16x32_bf16 v[54:57], v[170:173], v[190:193], v[54:57]
	v_mfma_f32_16x16x32_bf16 v[50:53], v[182:185], v[190:193], v[50:53]
	v_mfma_f32_16x16x32_bf16 v[38:41], v[170:173], v[198:201], v[38:41]
	v_mfma_f32_16x16x32_bf16 v[34:37], v[182:185], v[198:201], v[34:37]
	v_mfma_f32_16x16x32_bf16 v[22:25], v[170:173], v[206:209], v[22:25]
	v_mfma_f32_16x16x32_bf16 v[18:21], v[182:185], v[206:209], v[18:21]
	v_mfma_f32_16x16x32_bf16 v[6:9], v[170:173], v[214:217], v[6:9]
	v_mfma_f32_16x16x32_bf16 v[2:5], v[182:185], v[214:217], v[2:5]
	s_setprio 0
	s_add_i32 s89, s89, 2
	s_add_u32 s56, s56, 0x8000
	s_addc_u32 s57, s57, 0
	s_add_u32 s87, s87, 0x8000
	s_addc_u32 s88, s88, 0
.LBB0_196:
	s_barrier
	ds_read_b128 v[130:133], v161
	ds_read_b128 v[134:137], v161 offset:1024
	ds_read_b128 v[152:155], v161 offset:2048
	ds_read_b128 v[156:159], v161 offset:3072
	ds_read_b128 v[166:169], v162
	ds_read_b128 v[170:173], v162 offset:1024
	ds_read_b128 v[174:177], v162 offset:2048
	ds_read_b128 v[182:185], v162 offset:3072
	s_add_u32 s58, s56, 0xfff84000
	s_addc_u32 s59, s57, -1
	s_cmp_eq_u32 s89, 28
	s_cselect_b32 s70, s19, s58
	s_cselect_b32 s71, s5, s59
	s_cselect_b32 s60, s47, s87
	s_cselect_b32 s61, s17, s88
	s_add_u32 s58, s70, 0x4000
	s_addc_u32 s59, s71, 0
	v_lshl_add_u64 v[178:179], s[56:57], 0, v[138:139]
	s_add_i32 m0, s72, 0xc000
	ds_read_b128 v[186:189], v163
	ds_read_b128 v[190:193], v163 offset:1024
	ds_read_b128 v[194:197], v163 offset:2048
	ds_read_b128 v[198:201], v163 offset:3072
	ds_read_b128 v[202:205], v163 offset:4096
	ds_read_b128 v[206:209], v163 offset:5120
	ds_read_b128 v[210:213], v163 offset:6144
	ds_read_b128 v[214:217], v163 offset:7168
	global_load_lds_dwordx4 v[178:179], off
	v_lshl_add_u64 v[178:179], s[56:57], 0, v[146:147]
	s_add_i32 m0, s72, 0xe000
	s_nop 0
	global_load_lds_dwordx4 v[178:179], off
	s_waitcnt vmcnt(8)
	s_waitcnt lgkmcnt(0)
	s_barrier
; #define PG8_STAGE(bufoff, gbase, voff) do { _Pragma("unroll") for (int _i = 0; _i < 2; ++_i) \
;         __builtin_amdgcn_global_load_lds((const unsigned*)((const char*)(gbase) + (voff)[_i]), (PG8_LAS unsigned*)(lds + (bufoff) + ldsw + _i * 8192), 16, 0, 0); } while (0)
; #define PG8_LDA(dst, b, h) do { _Pragma("unroll") for (int m = 0; m < 4; ++m) _Pragma("unroll") for (int k = 0; k < 2; ++k) dst[m][k] = *(const PG8_LAS bf16x8*)(lds + PG8_SA(b, h) + aoff + m * 2048 + k * 1024); } while (0)
; #define PG8_LDB(dst, b, h) do { _Pragma("unroll") for (int n = 0; n < 2; ++n) _Pragma("unroll") for (int k = 0; k < 2; ++k) dst[n][k] = *(const PG8_LAS bf16x8*)(lds + PG8_SB(b, h) + boff + n * 2048 + k * 1024); } while (0)
; #define PG8_MMA(ai, bj, At, Bt) do { __builtin_amdgcn_s_setprio(1); _Pragma("unroll") for (int m = 0; m < 4; ++m) _Pragma("unroll") for (int n = 0; n < 2; ++n) _Pragma("unroll") for (int k = 0; k < 2; ++k) \
;         acc[ai][bj][m][n] = __builtin_amdgcn_mfma_f32_16x16x32_bf16(Bt[n][k], At[m][k], acc[ai][bj][m][n], 0, 0, 0); __builtin_amdgcn_s_setprio(0); } while (0)
; #define PG8_WAIT_V(n) asm volatile("s_waitcnt vmcnt(" #n ")" ::: "memory")
; #define PG8_WAIT_L(n) asm volatile("s_waitcnt lgkmcnt(" #n ")" ::: "memory")
; #define PG8_BAR __builtin_amdgcn_s_barrier()
; template <class Epi, class Sched, bool ALIGN_EPI = false, bool SP2 = false, bool RS = false, bool BPRE = false>
; __device__ __forceinline__ void gemm_phase(PG8_LAS unsigned char* lds, const Gemm g, const Sched& S, const Epi& E, const float* rs_ss = nullptr, PG8_LAS float* rs_tab = nullptr) {
;     ...
;             PG8_LDB(B0, 0, 0); PG8_LDB(B1, 0, 1); PG8_SCHED; PG8_LDA(At, 0, 0); PG8_STAGE(PG8_SA(1, 1), a1 + hstep, voffA);
;             PG8_WAIT_V(8); PG8_WAIT_L(0); PG8_BAR; PG8_MMA(0, 0, At, B0); PG8_MMA(0, 1, At, B1); PG8_BAR; PG8_SCHED;
;             PG8_LDA(At, 0, 1); PG8_STAGE(PG8_SB(0, 0), b2, voffB); PG8_STAGE(PG8_SB(0, 1), b2 + hstep, voffB); PG8_STAGE(PG8_SA(0, 0), a2, voffA);
;             PG8_WAIT_V(8); PG8_WAIT_L(0); PG8_BAR; PG8_MMA(1, 0, At, B0); PG8_MMA(1, 1, At, B1); PG8_BAR; PG8_SCHED;
;             PG8_LDB(B0, 1, 0); PG8_LDB(B1, 1, 1); PG8_SCHED; PG8_LDA(At, 1, 0); PG8_STAGE(PG8_SA(0, 1), a2 + hstep, voffA);
;             PG8_WAIT_V(8); PG8_WAIT_L(0); PG8_BAR; PG8_MMA(0, 0, At, B0); PG8_MMA(0, 1, At, B1); PG8_BAR; PG8_SCHED;
	s_setprio 1
	s_waitcnt lgkmcnt(0)
	v_mfma_f32_16x16x32_bf16 v[126:129], v[130:133], v[186:189], v[126:129]
	v_mfma_f32_16x16x32_bf16 v[122:125], v[152:155], v[186:189], v[122:125]
	v_mfma_f32_16x16x32_bf16 v[110:113], v[130:133], v[194:197], v[110:113]
	v_mfma_f32_16x16x32_bf16 v[106:109], v[152:155], v[194:197], v[106:109]
	v_mfma_f32_16x16x32_bf16 v[94:97], v[130:133], v[202:205], v[94:97]
	v_mfma_f32_16x16x32_bf16 v[90:93], v[152:155], v[202:205], v[90:93]
	v_mfma_f32_16x16x32_bf16 v[78:81], v[130:133], v[210:213], v[78:81]
	v_mfma_f32_16x16x32_bf16 v[74:77], v[152:155], v[210:213], v[74:77]
	v_mfma_f32_16x16x32_bf16 v[126:129], v[134:137], v[190:193], v[126:129]
	v_mfma_f32_16x16x32_bf16 v[122:125], v[156:159], v[190:193], v[122:125]
	v_mfma_f32_16x16x32_bf16 v[110:113], v[134:137], v[198:201], v[110:113]
	v_mfma_f32_16x16x32_bf16 v[106:109], v[156:159], v[198:201], v[106:109]
	v_mfma_f32_16x16x32_bf16 v[94:97], v[134:137], v[206:209], v[94:97]
	v_mfma_f32_16x16x32_bf16 v[90:93], v[156:159], v[206:209], v[90:93]
	v_mfma_f32_16x16x32_bf16 v[78:81], v[134:137], v[214:217], v[78:81]
	v_mfma_f32_16x16x32_bf16 v[74:77], v[156:159], v[214:217], v[74:77]
	s_setprio 0
	s_setprio 1
	v_mfma_f32_16x16x32_bf16 v[118:121], v[166:169], v[186:189], v[118:121]
	v_mfma_f32_16x16x32_bf16 v[114:117], v[174:177], v[186:189], v[114:117]
	v_mfma_f32_16x16x32_bf16 v[102:105], v[166:169], v[194:197], v[102:105]
	v_mfma_f32_16x16x32_bf16 v[98:101], v[174:177], v[194:197], v[98:101]
	v_mfma_f32_16x16x32_bf16 v[86:89], v[166:169], v[202:205], v[86:89]
	v_mfma_f32_16x16x32_bf16 v[82:85], v[174:177], v[202:205], v[82:85]
	v_mfma_f32_16x16x32_bf16 v[70:73], v[166:169], v[210:213], v[70:73]
	v_mfma_f32_16x16x32_bf16 v[66:69], v[174:177], v[210:213], v[66:69]
	v_mfma_f32_16x16x32_bf16 v[118:121], v[170:173], v[190:193], v[118:121]
	v_mfma_f32_16x16x32_bf16 v[114:117], v[182:185], v[190:193], v[114:117]
	v_mfma_f32_16x16x32_bf16 v[102:105], v[170:173], v[198:201], v[102:105]
	v_mfma_f32_16x16x32_bf16 v[98:101], v[182:185], v[198:201], v[98:101]
	v_mfma_f32_16x16x32_bf16 v[86:89], v[170:173], v[206:209], v[86:89]
	v_mfma_f32_16x16x32_bf16 v[82:85], v[182:185], v[206:209], v[82:85]
	v_mfma_f32_16x16x32_bf16 v[70:73], v[170:173], v[214:217], v[70:73]
	v_mfma_f32_16x16x32_bf16 v[66:69], v[182:185], v[214:217], v[66:69]
	s_setprio 0
	s_barrier
	s_add_i32 s90, s83, s15
	v_lshl_add_u64 v[178:179], s[60:61], 0, v[138:139]
	s_mov_b32 m0, s90
	ds_read_b128 v[186:189], v163 offset:16384
	ds_read_b128 v[190:193], v163 offset:17408
	ds_read_b128 v[194:197], v163 offset:18432
	ds_read_b128 v[198:201], v163 offset:19456
	ds_read_b128 v[202:205], v163 offset:20480
	ds_read_b128 v[206:209], v163 offset:21504
	ds_read_b128 v[210:213], v163 offset:22528
	ds_read_b128 v[214:217], v163 offset:23552
	global_load_lds_dwordx4 v[178:179], off
	s_add_i32 m0, s90, 0x2000
	s_add_u32 s90, s60, 0x80000
	v_lshl_add_u64 v[178:179], s[60:61], 0, v[140:141]
	s_addc_u32 s91, s61, 0
	s_add_i32 s92, s86, s15
	global_load_lds_dwordx4 v[178:179], off
	v_lshl_add_u64 v[178:179], s[90:91], 0, v[138:139]
	s_mov_b32 m0, s92
	s_nop 0
	global_load_lds_dwordx4 v[178:179], off
	v_lshl_add_u64 v[178:179], s[90:91], 0, v[140:141]
	s_add_i32 m0, s92, 0x2000
	s_nop 0
	global_load_lds_dwordx4 v[178:179], off
	v_lshl_add_u64 v[178:179], s[70:71], 0, v[138:139]
	s_mov_b32 m0, s72
	s_nop 0
	global_load_lds_dwordx4 v[178:179], off
	v_lshl_add_u64 v[178:179], s[70:71], 0, v[140:141]
	s_mov_b32 m0, s73
	s_nop 0
	global_load_lds_dwordx4 v[178:179], off
	s_waitcnt vmcnt(8)
	s_waitcnt lgkmcnt(0)
	s_barrier
	s_setprio 1
	s_waitcnt lgkmcnt(0)
	v_mfma_f32_16x16x32_bf16 v[62:65], v[130:133], v[186:189], v[62:65]
	v_mfma_f32_16x16x32_bf16 v[58:61], v[152:155], v[186:189], v[58:61]
	v_mfma_f32_16x16x32_bf16 v[46:49], v[130:133], v[194:197], v[46:49]
	v_mfma_f32_16x16x32_bf16 v[42:45], v[152:155], v[194:197], v[42:45]
	v_mfma_f32_16x16x32_bf16 v[30:33], v[130:133], v[202:205], v[30:33]
	v_mfma_f32_16x16x32_bf16 v[26:29], v[152:155], v[202:205], v[26:29]
	v_mfma_f32_16x16x32_bf16 v[14:17], v[130:133], v[210:213], v[14:17]
	v_mfma_f32_16x16x32_bf16 v[10:13], v[152:155], v[210:213], v[10:13]
	v_mfma_f32_16x16x32_bf16 v[62:65], v[134:137], v[190:193], v[62:65]
	v_mfma_f32_16x16x32_bf16 v[58:61], v[156:159], v[190:193], v[58:61]
	v_mfma_f32_16x16x32_bf16 v[46:49], v[134:137], v[198:201], v[46:49]
	v_mfma_f32_16x16x32_bf16 v[42:45], v[156:159], v[198:201], v[42:45]
	v_mfma_f32_16x16x32_bf16 v[30:33], v[134:137], v[206:209], v[30:33]
	v_mfma_f32_16x16x32_bf16 v[26:29], v[156:159], v[206:209], v[26:29]
	v_mfma_f32_16x16x32_bf16 v[14:17], v[134:137], v[214:217], v[14:17]
	v_mfma_f32_16x16x32_bf16 v[10:13], v[156:159], v[214:217], v[10:13]
	s_setprio 0
	s_setprio 1
	v_mfma_f32_16x16x32_bf16 v[54:57], v[166:169], v[186:189], v[54:57]
	v_mfma_f32_16x16x32_bf16 v[50:53], v[174:177], v[186:189], v[50:53]
	v_mfma_f32_16x16x32_bf16 v[38:41], v[166:169], v[194:197], v[38:41]
	v_mfma_f32_16x16x32_bf16 v[34:37], v[174:177], v[194:197], v[34:37]
	v_mfma_f32_16x16x32_bf16 v[22:25], v[166:169], v[202:205], v[22:25]
	v_mfma_f32_16x16x32_bf16 v[18:21], v[174:177], v[202:205], v[18:21]
	v_mfma_f32_16x16x32_bf16 v[6:9], v[166:169], v[210:213], v[6:9]
	v_mfma_f32_16x16x32_bf16 v[2:5], v[174:177], v[210:213], v[2:5]
	v_mfma_f32_16x16x32_bf16 v[54:57], v[170:173], v[190:193], v[54:57]
	v_mfma_f32_16x16x32_bf16 v[50:53], v[182:185], v[190:193], v[50:53]
	v_mfma_f32_16x16x32_bf16 v[38:41], v[170:173], v[198:201], v[38:41]
	v_mfma_f32_16x16x32_bf16 v[34:37], v[182:185], v[198:201], v[34:37]
	v_mfma_f32_16x16x32_bf16 v[22:25], v[170:173], v[206:209], v[22:25]
	v_mfma_f32_16x16x32_bf16 v[18:21], v[182:185], v[206:209], v[18:21]
	v_mfma_f32_16x16x32_bf16 v[6:9], v[170:173], v[214:217], v[6:9]
	v_mfma_f32_16x16x32_bf16 v[2:5], v[182:185], v[214:217], v[2:5]
	s_setprio 0
	s_barrier
; #define PG8_STAGE(bufoff, gbase, voff) do { _Pragma("unroll") for (int _i = 0; _i < 2; ++_i) \
;         __builtin_amdgcn_global_load_lds((const unsigned*)((const char*)(gbase) + (voff)[_i]), (PG8_LAS unsigned*)(lds + (bufoff) + ldsw + _i * 8192), 16, 0, 0); } while (0)
; #define PG8_LDA(dst, b, h) do { _Pragma("unroll") for (int m = 0; m < 4; ++m) _Pragma("unroll") for (int k = 0; k < 2; ++k) dst[m][k] = *(const PG8_LAS bf16x8*)(lds + PG8_SA(b, h) + aoff + m * 2048 + k * 1024); } while (0)
; #define PG8_LDB(dst, b, h) do { _Pragma("unroll") for (int n = 0; n < 2; ++n) _Pragma("unroll") for (int k = 0; k < 2; ++k) dst[n][k] = *(const PG8_LAS bf16x8*)(lds + PG8_SB(b, h) + boff + n * 2048 + k * 1024); } while (0)
; #define PG8_MMA(ai, bj, At, Bt) do { __builtin_amdgcn_s_setprio(1); _Pragma("unroll") for (int m = 0; m < 4; ++m) _Pragma("unroll") for (int n = 0; n < 2; ++n) _Pragma("unroll") for (int k = 0; k < 2; ++k) \
;         acc[ai][bj][m][n] = __builtin_amdgcn_mfma_f32_16x16x32_bf16(Bt[n][k], At[m][k], acc[ai][bj][m][n], 0, 0, 0); __builtin_amdgcn_s_setprio(0); } while (0)
; #define PG8_WAIT_V(n) asm volatile("s_waitcnt vmcnt(" #n ")" ::: "memory")
; #define PG8_WAIT_L(n) asm volatile("s_waitcnt lgkmcnt(" #n ")" ::: "memory")
; #define PG8_BAR __builtin_amdgcn_s_barrier()
; #define PG8_SCHED __builtin_amdgcn_sched_barrier(0)
; template <class Epi, class Sched, bool ALIGN_EPI = false, bool SP2 = false, bool RS = false, bool BPRE = false>
; __device__ __forceinline__ void gemm_phase(PG8_LAS unsigned char* lds, const Gemm g, const Sched& S, const Epi& E, const float* rs_ss = nullptr, PG8_LAS float* rs_tab = nullptr) {
;     ...
;             PG8_LDB(B0, 1, 0); PG8_LDB(B1, 1, 1); PG8_SCHED; PG8_LDA(At, 1, 0); PG8_STAGE(PG8_SA(0, 1), a2 + hstep, voffA);
;             PG8_WAIT_V(8); PG8_WAIT_L(0); PG8_BAR; PG8_MMA(0, 0, At, B0); PG8_MMA(0, 1, At, B1); PG8_BAR; PG8_SCHED;
	s_add_i32 s90, 0, 0x18000
	v_add_u32_e32 v143, s90, v160
	s_add_i32 s91, 0, 0x1c000
	ds_read_b128 v[130:133], v143
	ds_read_b128 v[134:137], v143 offset:1024
	ds_read_b128 v[152:155], v143 offset:2048
	ds_read_b128 v[156:159], v143 offset:3072
	v_add_u32_e32 v143, s91, v160
	ds_read_b128 v[166:169], v143
	ds_read_b128 v[170:173], v143 offset:1024
	ds_read_b128 v[174:177], v143 offset:2048
	ds_read_b128 v[182:185], v143 offset:3072
	s_add_u32 s70, s70, 0x80000
	s_addc_u32 s71, s71, 0
	s_mov_b32 m0, s74
	v_lshl_add_u64 v[178:179], s[70:71], 0, v[138:139]
	ds_read_b128 v[186:189], v163 offset:32768
	ds_read_b128 v[190:193], v163 offset:33792
	ds_read_b128 v[194:197], v163 offset:34816
	ds_read_b128 v[198:201], v163 offset:35840
	ds_read_b128 v[202:205], v163 offset:36864
	ds_read_b128 v[206:209], v163 offset:37888
	ds_read_b128 v[210:213], v163 offset:38912
	ds_read_b128 v[214:217], v163 offset:39936
	global_load_lds_dwordx4 v[178:179], off
	v_lshl_add_u64 v[178:179], s[70:71], 0, v[140:141]
	s_mov_b32 m0, s75
	s_nop 0
	global_load_lds_dwordx4 v[178:179], off
	s_waitcnt vmcnt(8)
	s_waitcnt lgkmcnt(0)
	s_barrier
	s_setprio 1
	s_waitcnt lgkmcnt(0)
	v_mfma_f32_16x16x32_bf16 v[126:129], v[130:133], v[186:189], v[126:129]
	v_mfma_f32_16x16x32_bf16 v[122:125], v[152:155], v[186:189], v[122:125]
	v_mfma_f32_16x16x32_bf16 v[110:113], v[130:133], v[194:197], v[110:113]
	v_mfma_f32_16x16x32_bf16 v[106:109], v[152:155], v[194:197], v[106:109]
	v_mfma_f32_16x16x32_bf16 v[94:97], v[130:133], v[202:205], v[94:97]
	v_mfma_f32_16x16x32_bf16 v[90:93], v[152:155], v[202:205], v[90:93]
	v_mfma_f32_16x16x32_bf16 v[78:81], v[130:133], v[210:213], v[78:81]
	v_mfma_f32_16x16x32_bf16 v[74:77], v[152:155], v[210:213], v[74:77]
	v_mfma_f32_16x16x32_bf16 v[126:129], v[134:137], v[190:193], v[126:129]
	v_mfma_f32_16x16x32_bf16 v[122:125], v[156:159], v[190:193], v[122:125]
	v_mfma_f32_16x16x32_bf16 v[110:113], v[134:137], v[198:201], v[110:113]
	v_mfma_f32_16x16x32_bf16 v[106:109], v[156:159], v[198:201], v[106:109]
	v_mfma_f32_16x16x32_bf16 v[94:97], v[134:137], v[206:209], v[94:97]
	v_mfma_f32_16x16x32_bf16 v[90:93], v[156:159], v[206:209], v[90:93]
	v_mfma_f32_16x16x32_bf16 v[78:81], v[134:137], v[214:217], v[78:81]
	v_mfma_f32_16x16x32_bf16 v[74:77], v[156:159], v[214:217], v[74:77]
	s_setprio 0
	s_setprio 1
	v_mfma_f32_16x16x32_bf16 v[118:121], v[166:169], v[186:189], v[118:121]
	v_mfma_f32_16x16x32_bf16 v[114:117], v[174:177], v[186:189], v[114:117]
	v_mfma_f32_16x16x32_bf16 v[102:105], v[166:169], v[194:197], v[102:105]
	v_mfma_f32_16x16x32_bf16 v[98:101], v[174:177], v[194:197], v[98:101]
	v_mfma_f32_16x16x32_bf16 v[86:89], v[166:169], v[202:205], v[86:89]
	v_mfma_f32_16x16x32_bf16 v[82:85], v[174:177], v[202:205], v[82:85]
	v_mfma_f32_16x16x32_bf16 v[70:73], v[166:169], v[210:213], v[70:73]
	v_mfma_f32_16x16x32_bf16 v[66:69], v[174:177], v[210:213], v[66:69]
	v_mfma_f32_16x16x32_bf16 v[118:121], v[170:173], v[190:193], v[118:121]
	v_mfma_f32_16x16x32_bf16 v[114:117], v[182:185], v[190:193], v[114:117]
	v_mfma_f32_16x16x32_bf16 v[102:105], v[170:173], v[198:201], v[102:105]
	v_mfma_f32_16x16x32_bf16 v[98:101], v[182:185], v[198:201], v[98:101]
	v_mfma_f32_16x16x32_bf16 v[86:89], v[170:173], v[206:209], v[86:89]
	v_mfma_f32_16x16x32_bf16 v[82:85], v[182:185], v[206:209], v[82:85]
	v_mfma_f32_16x16x32_bf16 v[70:73], v[170:173], v[214:217], v[70:73]
	v_mfma_f32_16x16x32_bf16 v[66:69], v[182:185], v[214:217], v[66:69]
	s_setprio 0
	s_barrier
; #define PG8_STAGE(bufoff, gbase, voff) do { _Pragma("unroll") for (int _i = 0; _i < 2; ++_i) \
;         __builtin_amdgcn_global_load_lds((const unsigned*)((const char*)(gbase) + (voff)[_i]), (PG8_LAS unsigned*)(lds + (bufoff) + ldsw + _i * 8192), 16, 0, 0); } while (0)
; #define PG8_LDA(dst, b, h) do { _Pragma("unroll") for (int m = 0; m < 4; ++m) _Pragma("unroll") for (int k = 0; k < 2; ++k) dst[m][k] = *(const PG8_LAS bf16x8*)(lds + PG8_SA(b, h) + aoff + m * 2048 + k * 1024); } while (0)
; #define PG8_MMA(ai, bj, At, Bt) do { __builtin_amdgcn_s_setprio(1); _Pragma("unroll") for (int m = 0; m < 4; ++m) _Pragma("unroll") for (int n = 0; n < 2; ++n) _Pragma("unroll") for (int k = 0; k < 2; ++k) \
;         acc[ai][bj][m][n] = __builtin_amdgcn_mfma_f32_16x16x32_bf16(Bt[n][k], At[m][k], acc[ai][bj][m][n], 0, 0, 0); __builtin_amdgcn_s_setprio(0); } while (0)
; #define PG8_WAIT_V(n) asm volatile("s_waitcnt vmcnt(" #n ")" ::: "memory")
; #define PG8_WAIT_L(n) asm volatile("s_waitcnt lgkmcnt(" #n ")" ::: "memory")
; #define PG8_BAR __builtin_amdgcn_s_barrier()
; #define PG8_SCHED __builtin_amdgcn_sched_barrier(0)
; template <class Epi, class Sched, bool ALIGN_EPI = false, bool SP2 = false, bool RS = false, bool BPRE = false>
; __device__ __forceinline__ void gemm_phase(PG8_LAS unsigned char* lds, const Gemm g, const Sched& S, const Epi& E, const float* rs_ss = nullptr, PG8_LAS float* rs_tab = nullptr) {
;     ...
;             PG8_LDA(At, 1, 1); PG8_STAGE(PG8_SB(1, 0), b3, voffB); PG8_STAGE(PG8_SB(1, 1), b3 + hstep, voffB); PG8_STAGE(PG8_SA(1, 0), a3, voffA);
;             PG8_WAIT_V(8); PG8_WAIT_L(0); PG8_BAR; PG8_MMA(1, 0, At, B0); PG8_MMA(1, 1, At, B1); PG8_BAR; PG8_SCHED;
;     ...
;         if constexpr (ALIGN_EPI) { if (wr == 0) PG8_BAR; }
	s_add_u32 s70, s60, 0x4000
	s_addc_u32 s71, s61, 0
	s_add_i32 s90, s90, s15
	v_lshl_add_u64 v[178:179], s[70:71], 0, v[138:139]
	s_mov_b32 m0, s90
	ds_read_b128 v[186:189], v163 offset:49152
	ds_read_b128 v[190:193], v163 offset:50176
	ds_read_b128 v[194:197], v163 offset:51200
	ds_read_b128 v[198:201], v163 offset:52224
	ds_read_b128 v[202:205], v163 offset:53248
	ds_read_b128 v[206:209], v163 offset:54272
	ds_read_b128 v[210:213], v163 offset:55296
	ds_read_b128 v[214:217], v163 offset:56320
	global_load_lds_dwordx4 v[178:179], off
	s_add_i32 m0, s90, 0x2000
	s_add_u32 s60, s60, 0x84000
	v_lshl_add_u64 v[178:179], s[70:71], 0, v[140:141]
	s_addc_u32 s61, s61, 0
	s_add_i32 s70, s91, s15
	global_load_lds_dwordx4 v[178:179], off
	v_lshl_add_u64 v[178:179], s[60:61], 0, v[138:139]
	s_mov_b32 m0, s70
	s_nop 0
	global_load_lds_dwordx4 v[178:179], off
	v_lshl_add_u64 v[178:179], s[60:61], 0, v[140:141]
	s_add_i32 m0, s70, 0x2000
	s_nop 0
	global_load_lds_dwordx4 v[178:179], off
	v_lshl_add_u64 v[178:179], s[58:59], 0, v[138:139]
	s_mov_b32 m0, s79
	s_nop 0
	global_load_lds_dwordx4 v[178:179], off
	v_lshl_add_u64 v[178:179], s[58:59], 0, v[140:141]
	s_mov_b32 m0, s80
	s_nop 0
	global_load_lds_dwordx4 v[178:179], off
	s_waitcnt vmcnt(8)
	s_waitcnt lgkmcnt(0)
	s_barrier
	s_setprio 1
	s_waitcnt lgkmcnt(0)
	v_mfma_f32_16x16x32_bf16 v[62:65], v[130:133], v[186:189], v[62:65]
	v_mfma_f32_16x16x32_bf16 v[58:61], v[152:155], v[186:189], v[58:61]
	v_mfma_f32_16x16x32_bf16 v[46:49], v[130:133], v[194:197], v[46:49]
	v_mfma_f32_16x16x32_bf16 v[42:45], v[152:155], v[194:197], v[42:45]
	v_mfma_f32_16x16x32_bf16 v[30:33], v[130:133], v[202:205], v[30:33]
	v_mfma_f32_16x16x32_bf16 v[26:29], v[152:155], v[202:205], v[26:29]
	v_mfma_f32_16x16x32_bf16 v[14:17], v[130:133], v[210:213], v[14:17]
	v_mfma_f32_16x16x32_bf16 v[10:13], v[152:155], v[210:213], v[10:13]
	v_mfma_f32_16x16x32_bf16 v[62:65], v[134:137], v[190:193], v[62:65]
	v_mfma_f32_16x16x32_bf16 v[58:61], v[156:159], v[190:193], v[58:61]
	v_mfma_f32_16x16x32_bf16 v[46:49], v[134:137], v[198:201], v[46:49]
	v_mfma_f32_16x16x32_bf16 v[42:45], v[156:159], v[198:201], v[42:45]
	v_mfma_f32_16x16x32_bf16 v[30:33], v[134:137], v[206:209], v[30:33]
	v_mfma_f32_16x16x32_bf16 v[26:29], v[156:159], v[206:209], v[26:29]
	v_mfma_f32_16x16x32_bf16 v[14:17], v[134:137], v[214:217], v[14:17]
	v_mfma_f32_16x16x32_bf16 v[10:13], v[156:159], v[214:217], v[10:13]
	s_setprio 0
	s_setprio 1
	v_mfma_f32_16x16x32_bf16 v[54:57], v[166:169], v[186:189], v[54:57]
	v_mfma_f32_16x16x32_bf16 v[50:53], v[174:177], v[186:189], v[50:53]
	v_mfma_f32_16x16x32_bf16 v[38:41], v[166:169], v[194:197], v[38:41]
	v_mfma_f32_16x16x32_bf16 v[34:37], v[174:177], v[194:197], v[34:37]
	v_mfma_f32_16x16x32_bf16 v[22:25], v[166:169], v[202:205], v[22:25]
	v_mfma_f32_16x16x32_bf16 v[18:21], v[174:177], v[202:205], v[18:21]
	v_mfma_f32_16x16x32_bf16 v[6:9], v[166:169], v[210:213], v[6:9]
	v_mfma_f32_16x16x32_bf16 v[2:5], v[174:177], v[210:213], v[2:5]
	v_mfma_f32_16x16x32_bf16 v[54:57], v[170:173], v[190:193], v[54:57]
	v_mfma_f32_16x16x32_bf16 v[50:53], v[182:185], v[190:193], v[50:53]
	v_mfma_f32_16x16x32_bf16 v[38:41], v[170:173], v[198:201], v[38:41]
	v_mfma_f32_16x16x32_bf16 v[34:37], v[182:185], v[198:201], v[34:37]
	v_mfma_f32_16x16x32_bf16 v[22:25], v[170:173], v[206:209], v[22:25]
	v_mfma_f32_16x16x32_bf16 v[18:21], v[182:185], v[206:209], v[18:21]
	v_mfma_f32_16x16x32_bf16 v[6:9], v[170:173], v[214:217], v[6:9]
	v_mfma_f32_16x16x32_bf16 v[2:5], v[182:185], v[214:217], v[2:5]
	s_setprio 0
	s_add_i32 s89, s89, 2
	s_add_u32 s56, s56, 0x8000
	s_addc_u32 s57, s57, 0
	s_add_u32 s87, s87, 0x8000
	s_addc_u32 s88, s88, 0
	s_cmp_gt_u32 s89, 29
	s_cbranch_scc0 .LBB0_196
	s_barrier
	s_and_b64 vcc, exec, s[12:13]
	s_cbranch_vccz .LBB0_199
	s_barrier

; #define PG8_LAS __attribute__((address_space(3)))
; template <class Epi, class Sched, bool ALIGN_EPI = false, bool SP2 = false, bool RS = false, bool BPRE = false>
; __device__ __forceinline__ void gemm_phase(PG8_LAS unsigned char* lds, const Gemm g, const Sched& S, const Epi& E, const float* rs_ss = nullptr, PG8_LAS float* rs_tab = nullptr) {
;     ...
;             if constexpr (RS) { if (t == 16 || t == 32) { const PG8_LAS float* tp = rs_tab + (ui & 1) * 768 + (t == 32 ? 256 : 0);
;                 _Pragma("unroll") for (int a = 0; a < 2; ++a) _Pragma("unroll") for (int m = 0; m < 4; ++m) { const float f = tp[a * HALF + wr * 64 + m * 16 + fr];
;                     _Pragma("unroll") for (int b = 0; b < 2; ++b) _Pragma("unroll") for (int n = 0; n < 2; ++n) acc[a][b][m][n] = acc[a][b][m][n] * f; } } }
.LBB0_753:
	s_and_b32 s38, s73, 15
	s_cmp_lg_u32 s38, 0
	s_cbranch_scc1 .LBB0_752
	s_cmp_eq_u32 s6, 0x80000
	s_cselect_b32 s38, 0x400, 0
	v_add_u32_e32 v3, s38, v158
	ds_read2_b32 v[4:5], v3 offset1:16
	ds_read2_b32 v[160:161], v3 offset0:32 offset1:48
	s_waitcnt lgkmcnt(0)
	v_pk_mul_f32 v[132:133], v[132:133], v[4:5] op_sel_hi:[1,0]
	v_pk_mul_f32 v[130:131], v[130:131], v[4:5] op_sel_hi:[1,0]
	v_pk_mul_f32 v[128:129], v[128:129], v[4:5] op_sel_hi:[1,0]
	v_pk_mul_f32 v[126:127], v[126:127], v[4:5] op_sel_hi:[1,0]
	v_pk_mul_f32 v[124:125], v[124:125], v[4:5] op_sel_hi:[1,0]
	v_pk_mul_f32 v[122:123], v[122:123], v[4:5] op_sel_hi:[1,0]
	v_pk_mul_f32 v[120:121], v[120:121], v[4:5] op_sel_hi:[1,0]
	v_pk_mul_f32 v[118:119], v[118:119], v[4:5] op_sel_hi:[1,0]
	v_mov_b32_e32 v4, v5
	v_pk_mul_f32 v[116:117], v[116:117], v[4:5] op_sel_hi:[1,0]
	v_pk_mul_f32 v[114:115], v[114:115], v[4:5] op_sel_hi:[1,0]
	v_pk_mul_f32 v[112:113], v[112:113], v[4:5] op_sel_hi:[1,0]
	v_pk_mul_f32 v[110:111], v[110:111], v[4:5] op_sel_hi:[1,0]
	v_pk_mul_f32 v[108:109], v[108:109], v[4:5] op_sel_hi:[1,0]
	v_pk_mul_f32 v[106:107], v[106:107], v[4:5] op_sel_hi:[1,0]
	v_pk_mul_f32 v[104:105], v[104:105], v[4:5] op_sel_hi:[1,0]
	v_pk_mul_f32 v[102:103], v[102:103], v[4:5] op_sel_hi:[1,0]
	v_pk_mul_f32 v[100:101], v[100:101], v[160:161] op_sel_hi:[1,0]
	v_pk_mul_f32 v[98:99], v[98:99], v[160:161] op_sel_hi:[1,0]
	v_pk_mul_f32 v[96:97], v[96:97], v[160:161] op_sel_hi:[1,0]
	v_pk_mul_f32 v[94:95], v[94:95], v[160:161] op_sel_hi:[1,0]
	v_pk_mul_f32 v[92:93], v[92:93], v[160:161] op_sel_hi:[1,0]
	v_pk_mul_f32 v[90:91], v[90:91], v[160:161] op_sel_hi:[1,0]
	v_pk_mul_f32 v[88:89], v[88:89], v[160:161] op_sel_hi:[1,0]
	v_pk_mul_f32 v[86:87], v[86:87], v[160:161] op_sel_hi:[1,0]
	v_mov_b32_e32 v4, v161
	ds_read2_b32 v[160:161], v3 offset0:128 offset1:144
	v_pk_mul_f32 v[84:85], v[84:85], v[4:5] op_sel_hi:[1,0]
	v_pk_mul_f32 v[82:83], v[82:83], v[4:5] op_sel_hi:[1,0]
	v_pk_mul_f32 v[80:81], v[80:81], v[4:5] op_sel_hi:[1,0]
	v_pk_mul_f32 v[78:79], v[78:79], v[4:5] op_sel_hi:[1,0]
	v_pk_mul_f32 v[76:77], v[76:77], v[4:5] op_sel_hi:[1,0]
	v_pk_mul_f32 v[74:75], v[74:75], v[4:5] op_sel_hi:[1,0]
	v_pk_mul_f32 v[72:73], v[72:73], v[4:5] op_sel_hi:[1,0]
	v_pk_mul_f32 v[70:71], v[70:71], v[4:5] op_sel_hi:[1,0]
	s_waitcnt lgkmcnt(0)
	v_pk_mul_f32 v[68:69], v[68:69], v[160:161] op_sel_hi:[1,0]
	v_pk_mul_f32 v[66:67], v[66:67], v[160:161] op_sel_hi:[1,0]
	v_pk_mul_f32 v[64:65], v[64:65], v[160:161] op_sel_hi:[1,0]
	v_pk_mul_f32 v[62:63], v[62:63], v[160:161] op_sel_hi:[1,0]
	v_pk_mul_f32 v[60:61], v[60:61], v[160:161] op_sel_hi:[1,0]
	v_pk_mul_f32 v[58:59], v[58:59], v[160:161] op_sel_hi:[1,0]
	v_pk_mul_f32 v[56:57], v[56:57], v[160:161] op_sel_hi:[1,0]
	v_pk_mul_f32 v[54:55], v[54:55], v[160:161] op_sel_hi:[1,0]
	v_mov_b32_e32 v4, v161
	ds_read2_b32 v[160:161], v3 offset0:160 offset1:176
	v_pk_mul_f32 v[52:53], v[52:53], v[4:5] op_sel_hi:[1,0]
	v_pk_mul_f32 v[50:51], v[50:51], v[4:5] op_sel_hi:[1,0]
	v_pk_mul_f32 v[48:49], v[48:49], v[4:5] op_sel_hi:[1,0]
	v_pk_mul_f32 v[46:47], v[46:47], v[4:5] op_sel_hi:[1,0]
	v_pk_mul_f32 v[44:45], v[44:45], v[4:5] op_sel_hi:[1,0]
	v_pk_mul_f32 v[42:43], v[42:43], v[4:5] op_sel_hi:[1,0]
	v_pk_mul_f32 v[40:41], v[40:41], v[4:5] op_sel_hi:[1,0]
	v_pk_mul_f32 v[38:39], v[38:39], v[4:5] op_sel_hi:[1,0]
	s_waitcnt lgkmcnt(0)
	v_mov_b32_e32 v4, v161
	v_pk_mul_f32 v[36:37], v[36:37], v[160:161] op_sel_hi:[1,0]
	v_pk_mul_f32 v[34:35], v[34:35], v[160:161] op_sel_hi:[1,0]
	v_pk_mul_f32 v[32:33], v[32:33], v[160:161] op_sel_hi:[1,0]
	v_pk_mul_f32 v[30:31], v[30:31], v[160:161] op_sel_hi:[1,0]
	v_pk_mul_f32 v[28:29], v[28:29], v[160:161] op_sel_hi:[1,0]
	v_pk_mul_f32 v[26:27], v[26:27], v[160:161] op_sel_hi:[1,0]
	v_pk_mul_f32 v[24:25], v[24:25], v[160:161] op_sel_hi:[1,0]
	v_pk_mul_f32 v[22:23], v[22:23], v[160:161] op_sel_hi:[1,0]
	v_pk_mul_f32 v[20:21], v[20:21], v[4:5] op_sel_hi:[1,0]
	v_pk_mul_f32 v[18:19], v[18:19], v[4:5] op_sel_hi:[1,0]
	v_pk_mul_f32 v[16:17], v[16:17], v[4:5] op_sel_hi:[1,0]
	v_pk_mul_f32 v[14:15], v[14:15], v[4:5] op_sel_hi:[1,0]
	v_pk_mul_f32 v[12:13], v[12:13], v[4:5] op_sel_hi:[1,0]
	v_pk_mul_f32 v[10:11], v[10:11], v[4:5] op_sel_hi:[1,0]
	v_pk_mul_f32 v[8:9], v[8:9], v[4:5] op_sel_hi:[1,0]
	v_pk_mul_f32 v[6:7], v[6:7], v[4:5] op_sel_hi:[1,0]
	s_branch .LBB0_752
